# attention epilogue: issue all 8 gate loads together instead of 8 serialized load-wait-store rounds
# speedup vs baseline: 1.0103x; 1.0103x over previous
.LBB0_107:
	ds_bpermute_b32 v2, v2, v1
	v_readlane_b32 s64, v247, 53
	v_readlane_b32 s72, v247, 61
	v_readlane_b32 s65, v247, 54
	v_readlane_b32 s66, v247, 55
	s_waitcnt lgkmcnt(0)
	v_add_f32_e32 v1, v1, v2
	v_div_scale_f32 v2, s[0:1], v1, v1, 1.0
	v_rcp_f32_e32 v3, v2
	v_readlane_b32 s67, v247, 56
	v_readlane_b32 s68, v247, 57
	v_readlane_b32 s69, v247, 58
	v_fma_f32 v4, -v2, v3, 1.0
	v_fmac_f32_e32 v3, v4, v3
	v_div_scale_f32 v4, vcc, 1.0, v1, 1.0
	v_mul_f32_e32 v5, v4, v3
	v_fma_f32 v6, -v2, v5, v4
	v_fmac_f32_e32 v5, v6, v3
	v_fma_f32 v2, -v2, v5, v4
	v_div_fmas_f32 v2, v2, v3, v5
	v_lshlrev_b32_e32 v4, 1, v120
	v_mov_b32_e32 v5, v0
	v_lshl_add_u64 v[4:5], v[112:113], 0, v[4:5]
	global_load_dwordx2 v[6:7], v[4:5], off offset:1536
	global_load_dwordx2 v[154:155], v[4:5], off offset:1552
	global_load_dwordx2 v[156:157], v[4:5], off offset:1568
	global_load_dwordx2 v[158:159], v[4:5], off offset:1584
	global_load_dwordx2 v[160:161], v[4:5], off offset:1600
	global_load_dwordx2 v[162:163], v[4:5], off offset:1616
	global_load_dwordx2 v[164:165], v[4:5], off offset:1632
	global_load_dwordx2 v[166:167], v[4:5], off offset:1648
	v_div_fixup_f32 v2, v2, v1, 1.0
	v_pk_mul_f32 v[12:13], v[32:33], v[2:3] op_sel_hi:[1,0]
	v_readlane_b32 s70, v247, 59
	v_readlane_b32 s71, v247, 60
	v_readlane_b32 s74, v247, 63
	v_readlane_b32 s75, v246, 0
	v_readlane_b32 s76, v246, 1
	v_readlane_b32 s77, v246, 2
	v_readlane_b32 s78, v246, 3
	v_readlane_b32 s79, v246, 4
	v_readlane_b32 s72, v246, 60
	v_readlane_b32 s73, v247, 62
	s_waitcnt vmcnt(0)
	v_lshlrev_b32_e32 v8, 16, v6
	v_mul_f32_e32 v1, 0xbfb8aa3b, v8
	v_exp_f32_e32 v1, v1
	v_and_b32_e32 v9, 0xffff0000, v6
	v_add_f32_e32 v1, 1.0, v1
	v_rcp_f32_e32 v10, v1
	v_mul_f32_e32 v1, 0xbfb8aa3b, v9
	v_exp_f32_e32 v1, v1
	s_nop 0
	v_add_f32_e32 v1, 1.0, v1
	v_rcp_f32_e32 v11, v1
	s_nop 0
	v_pk_mul_f32 v[8:9], v[10:11], v[8:9]
	s_nop 0
	v_pk_mul_f32 v[8:9], v[12:13], v[8:9]
	v_pk_mul_f32 v[12:13], v[34:35], v[2:3] op_sel_hi:[1,0]
	v_cvt_pk_bf16_f32 v6, v8, v9
	v_lshlrev_b32_e32 v8, 16, v7
	v_mul_f32_e32 v1, 0xbfb8aa3b, v8
	v_exp_f32_e32 v1, v1
	v_and_b32_e32 v9, 0xffff0000, v7
	v_add_f32_e32 v1, 1.0, v1
	v_rcp_f32_e32 v10, v1
	v_mul_f32_e32 v1, 0xbfb8aa3b, v9
	v_exp_f32_e32 v1, v1
	s_nop 0
	v_add_f32_e32 v1, 1.0, v1
	v_rcp_f32_e32 v11, v1
	s_nop 0
	v_pk_mul_f32 v[8:9], v[10:11], v[8:9]
	s_nop 0
	v_pk_mul_f32 v[8:9], v[12:13], v[8:9]
	v_pk_mul_f32 v[12:13], v[36:37], v[2:3] op_sel_hi:[1,0]
	v_cvt_pk_bf16_f32 v7, v8, v9
	global_store_dwordx2 v[4:5], v[6:7], off
	v_mov_b32_e32 v6, v154
	v_mov_b32_e32 v7, v155
	v_lshlrev_b32_e32 v8, 16, v6
	v_mul_f32_e32 v1, 0xbfb8aa3b, v8
	v_exp_f32_e32 v1, v1
	v_and_b32_e32 v9, 0xffff0000, v6
	v_add_f32_e32 v1, 1.0, v1
	v_rcp_f32_e32 v10, v1
	v_mul_f32_e32 v1, 0xbfb8aa3b, v9
	v_exp_f32_e32 v1, v1
	s_nop 0
	v_add_f32_e32 v1, 1.0, v1
	v_rcp_f32_e32 v11, v1
	s_nop 0
	v_pk_mul_f32 v[8:9], v[10:11], v[8:9]
	s_nop 0
	v_pk_mul_f32 v[8:9], v[12:13], v[8:9]
	v_pk_mul_f32 v[12:13], v[38:39], v[2:3] op_sel_hi:[1,0]
	v_cvt_pk_bf16_f32 v6, v8, v9
	v_lshlrev_b32_e32 v8, 16, v7
	v_mul_f32_e32 v1, 0xbfb8aa3b, v8
	v_exp_f32_e32 v1, v1
	v_and_b32_e32 v9, 0xffff0000, v7
	v_add_f32_e32 v1, 1.0, v1
	v_rcp_f32_e32 v10, v1
	v_mul_f32_e32 v1, 0xbfb8aa3b, v9
	v_exp_f32_e32 v1, v1
	s_nop 0
	v_add_f32_e32 v1, 1.0, v1
	v_rcp_f32_e32 v11, v1
	s_nop 0
	v_pk_mul_f32 v[8:9], v[10:11], v[8:9]
	s_nop 0
	v_pk_mul_f32 v[8:9], v[12:13], v[8:9]
	v_pk_mul_f32 v[12:13], v[40:41], v[2:3] op_sel_hi:[1,0]
	v_cvt_pk_bf16_f32 v7, v8, v9
	global_store_dwordx2 v[4:5], v[6:7], off offset:16
	v_mov_b32_e32 v6, v156
	v_mov_b32_e32 v7, v157
	v_lshlrev_b32_e32 v8, 16, v6
	v_mul_f32_e32 v1, 0xbfb8aa3b, v8
	v_exp_f32_e32 v1, v1
	v_and_b32_e32 v9, 0xffff0000, v6
	v_add_f32_e32 v1, 1.0, v1
	v_rcp_f32_e32 v10, v1
	v_mul_f32_e32 v1, 0xbfb8aa3b, v9
	v_exp_f32_e32 v1, v1
	s_nop 0
	v_add_f32_e32 v1, 1.0, v1
	v_rcp_f32_e32 v11, v1
	s_nop 0
	v_pk_mul_f32 v[8:9], v[10:11], v[8:9]
	s_nop 0
	v_pk_mul_f32 v[8:9], v[12:13], v[8:9]
	v_pk_mul_f32 v[12:13], v[42:43], v[2:3] op_sel_hi:[1,0]
	v_cvt_pk_bf16_f32 v6, v8, v9
	v_lshlrev_b32_e32 v8, 16, v7
	v_mul_f32_e32 v1, 0xbfb8aa3b, v8
	v_exp_f32_e32 v1, v1
	v_and_b32_e32 v9, 0xffff0000, v7
	v_add_f32_e32 v1, 1.0, v1
	v_rcp_f32_e32 v10, v1
	v_mul_f32_e32 v1, 0xbfb8aa3b, v9
	v_exp_f32_e32 v1, v1
	s_nop 0
	v_add_f32_e32 v1, 1.0, v1
	v_rcp_f32_e32 v11, v1
	s_nop 0
	v_pk_mul_f32 v[8:9], v[10:11], v[8:9]
	s_nop 0
	v_pk_mul_f32 v[8:9], v[12:13], v[8:9]
	v_pk_mul_f32 v[12:13], v[44:45], v[2:3] op_sel_hi:[1,0]
	v_cvt_pk_bf16_f32 v7, v8, v9
	global_store_dwordx2 v[4:5], v[6:7], off offset:32
	v_mov_b32_e32 v6, v158
	v_mov_b32_e32 v7, v159
	v_lshlrev_b32_e32 v8, 16, v6
	v_mul_f32_e32 v1, 0xbfb8aa3b, v8
	v_exp_f32_e32 v1, v1
	v_and_b32_e32 v9, 0xffff0000, v6
	v_add_f32_e32 v1, 1.0, v1
	v_rcp_f32_e32 v10, v1
	v_mul_f32_e32 v1, 0xbfb8aa3b, v9
	v_exp_f32_e32 v1, v1
	s_nop 0
	v_add_f32_e32 v1, 1.0, v1
	v_rcp_f32_e32 v11, v1
	s_nop 0
	v_pk_mul_f32 v[8:9], v[10:11], v[8:9]
	s_nop 0
	v_pk_mul_f32 v[8:9], v[12:13], v[8:9]
	v_pk_mul_f32 v[12:13], v[46:47], v[2:3] op_sel_hi:[1,0]
	v_cvt_pk_bf16_f32 v6, v8, v9
	v_lshlrev_b32_e32 v8, 16, v7
	v_mul_f32_e32 v1, 0xbfb8aa3b, v8
	v_exp_f32_e32 v1, v1
	v_and_b32_e32 v9, 0xffff0000, v7
	v_add_f32_e32 v1, 1.0, v1
	v_rcp_f32_e32 v10, v1
	v_mul_f32_e32 v1, 0xbfb8aa3b, v9
	v_exp_f32_e32 v1, v1
	s_nop 0
	v_add_f32_e32 v1, 1.0, v1
	v_rcp_f32_e32 v11, v1
	s_nop 0
	v_pk_mul_f32 v[8:9], v[10:11], v[8:9]
	s_nop 0
	v_pk_mul_f32 v[8:9], v[12:13], v[8:9]
	v_pk_mul_f32 v[12:13], v[16:17], v[2:3] op_sel_hi:[1,0]
	v_cvt_pk_bf16_f32 v7, v8, v9
	global_store_dwordx2 v[4:5], v[6:7], off offset:48
	v_mov_b32_e32 v6, v160
	v_mov_b32_e32 v7, v161
	v_lshlrev_b32_e32 v8, 16, v6
	v_mul_f32_e32 v1, 0xbfb8aa3b, v8
	v_exp_f32_e32 v1, v1
	v_and_b32_e32 v9, 0xffff0000, v6
	v_add_f32_e32 v1, 1.0, v1
	v_rcp_f32_e32 v10, v1
	v_mul_f32_e32 v1, 0xbfb8aa3b, v9
	v_exp_f32_e32 v1, v1
	s_nop 0
	v_add_f32_e32 v1, 1.0, v1
	v_rcp_f32_e32 v11, v1
	s_nop 0
	v_pk_mul_f32 v[8:9], v[10:11], v[8:9]
	s_nop 0
	v_pk_mul_f32 v[8:9], v[12:13], v[8:9]
	v_pk_mul_f32 v[12:13], v[18:19], v[2:3] op_sel_hi:[1,0]
	v_cvt_pk_bf16_f32 v6, v8, v9
	v_lshlrev_b32_e32 v8, 16, v7
	v_mul_f32_e32 v1, 0xbfb8aa3b, v8
	v_exp_f32_e32 v1, v1
	v_and_b32_e32 v9, 0xffff0000, v7
	v_add_f32_e32 v1, 1.0, v1
	v_rcp_f32_e32 v10, v1
	v_mul_f32_e32 v1, 0xbfb8aa3b, v9
	v_exp_f32_e32 v1, v1
	s_nop 0
	v_add_f32_e32 v1, 1.0, v1
	v_rcp_f32_e32 v11, v1
	s_nop 0
	v_pk_mul_f32 v[8:9], v[10:11], v[8:9]
	s_nop 0
	v_pk_mul_f32 v[8:9], v[12:13], v[8:9]
	v_pk_mul_f32 v[12:13], v[20:21], v[2:3] op_sel_hi:[1,0]
	v_cvt_pk_bf16_f32 v7, v8, v9
	global_store_dwordx2 v[4:5], v[6:7], off offset:64
	v_mov_b32_e32 v6, v162
	v_mov_b32_e32 v7, v163
	v_lshlrev_b32_e32 v8, 16, v6
	v_mul_f32_e32 v1, 0xbfb8aa3b, v8
	v_exp_f32_e32 v1, v1
	v_and_b32_e32 v9, 0xffff0000, v6
	v_add_f32_e32 v1, 1.0, v1
	v_rcp_f32_e32 v10, v1
	v_mul_f32_e32 v1, 0xbfb8aa3b, v9
	v_exp_f32_e32 v1, v1
	s_nop 0
	v_add_f32_e32 v1, 1.0, v1
	v_rcp_f32_e32 v11, v1
	s_nop 0
	v_pk_mul_f32 v[8:9], v[10:11], v[8:9]
	s_nop 0
	v_pk_mul_f32 v[8:9], v[12:13], v[8:9]
	v_pk_mul_f32 v[12:13], v[22:23], v[2:3] op_sel_hi:[1,0]
	v_cvt_pk_bf16_f32 v6, v8, v9
	v_lshlrev_b32_e32 v8, 16, v7
	v_mul_f32_e32 v1, 0xbfb8aa3b, v8
	v_exp_f32_e32 v1, v1
	v_and_b32_e32 v9, 0xffff0000, v7
	v_add_f32_e32 v1, 1.0, v1
	v_rcp_f32_e32 v10, v1
	v_mul_f32_e32 v1, 0xbfb8aa3b, v9
	v_exp_f32_e32 v1, v1
	s_nop 0
	v_add_f32_e32 v1, 1.0, v1
	v_rcp_f32_e32 v11, v1
	s_nop 0
	v_pk_mul_f32 v[8:9], v[10:11], v[8:9]
	s_nop 0
	v_pk_mul_f32 v[8:9], v[12:13], v[8:9]
	v_pk_mul_f32 v[12:13], v[24:25], v[2:3] op_sel_hi:[1,0]
	v_cvt_pk_bf16_f32 v7, v8, v9
	global_store_dwordx2 v[4:5], v[6:7], off offset:80
	v_mov_b32_e32 v6, v164
	v_mov_b32_e32 v7, v165
	v_lshlrev_b32_e32 v8, 16, v6
	v_mul_f32_e32 v1, 0xbfb8aa3b, v8
	v_exp_f32_e32 v1, v1
	v_and_b32_e32 v9, 0xffff0000, v6
	v_add_f32_e32 v1, 1.0, v1
	v_rcp_f32_e32 v10, v1
	v_mul_f32_e32 v1, 0xbfb8aa3b, v9
	v_exp_f32_e32 v1, v1
	s_nop 0
	v_add_f32_e32 v1, 1.0, v1
	v_rcp_f32_e32 v11, v1
	s_nop 0
	v_pk_mul_f32 v[8:9], v[10:11], v[8:9]
	s_nop 0
	v_pk_mul_f32 v[8:9], v[12:13], v[8:9]
	v_pk_mul_f32 v[12:13], v[26:27], v[2:3] op_sel_hi:[1,0]
	v_cvt_pk_bf16_f32 v6, v8, v9
	v_lshlrev_b32_e32 v8, 16, v7
	v_mul_f32_e32 v1, 0xbfb8aa3b, v8
	v_exp_f32_e32 v1, v1
	v_and_b32_e32 v9, 0xffff0000, v7
	v_add_f32_e32 v1, 1.0, v1
	v_rcp_f32_e32 v10, v1
	v_mul_f32_e32 v1, 0xbfb8aa3b, v9
	v_exp_f32_e32 v1, v1
	s_nop 0
	v_add_f32_e32 v1, 1.0, v1
	v_rcp_f32_e32 v11, v1
	s_nop 0
	v_pk_mul_f32 v[8:9], v[10:11], v[8:9]
	s_nop 0
	v_pk_mul_f32 v[8:9], v[12:13], v[8:9]
	v_pk_mul_f32 v[12:13], v[28:29], v[2:3] op_sel_hi:[1,0]
	v_cvt_pk_bf16_f32 v7, v8, v9
	global_store_dwordx2 v[4:5], v[6:7], off offset:96
	v_mov_b32_e32 v6, v166
	v_mov_b32_e32 v7, v167
	v_pk_mul_f32 v[2:3], v[30:31], v[2:3] op_sel_hi:[1,0]
	v_lshlrev_b32_e32 v8, 16, v6
	v_mul_f32_e32 v1, 0xbfb8aa3b, v8
	v_exp_f32_e32 v1, v1
	v_and_b32_e32 v9, 0xffff0000, v6
	v_add_f32_e32 v1, 1.0, v1
	v_rcp_f32_e32 v10, v1
	v_mul_f32_e32 v1, 0xbfb8aa3b, v9
	v_exp_f32_e32 v1, v1
	s_nop 0
	v_add_f32_e32 v1, 1.0, v1
	v_rcp_f32_e32 v11, v1
	s_nop 0
	v_pk_mul_f32 v[8:9], v[10:11], v[8:9]
	s_nop 0
	v_pk_mul_f32 v[8:9], v[12:13], v[8:9]
	s_nop 0
	v_cvt_pk_bf16_f32 v6, v8, v9
	v_lshlrev_b32_e32 v8, 16, v7
	v_mul_f32_e32 v1, 0xbfb8aa3b, v8
	v_exp_f32_e32 v1, v1
	v_and_b32_e32 v9, 0xffff0000, v7
	v_add_f32_e32 v1, 1.0, v1
	v_rcp_f32_e32 v10, v1
	v_mul_f32_e32 v1, 0xbfb8aa3b, v9
	v_exp_f32_e32 v1, v1
	s_nop 0
	v_add_f32_e32 v1, 1.0, v1
	v_rcp_f32_e32 v11, v1
	s_nop 0
	v_pk_mul_f32 v[8:9], v[10:11], v[8:9]
	s_nop 0
	v_pk_mul_f32 v[2:3], v[2:3], v[8:9]
	s_nop 0
	v_cvt_pk_bf16_f32 v7, v2, v3
	global_store_dwordx2 v[4:5], v[6:7], off offset:112

.LBB0_143:
	v_and_b32_e32 v2, 64, v223
	v_xor_b32_e32 v1, 32, v223
	v_add_u32_e32 v2, 64, v2
	v_cmp_lt_i32_e32 vcc, v1, v2
	v_readlane_b32 s64, v247, 53
	v_readlane_b32 s72, v247, 61
	v_cndmask_b32_e32 v1, v223, v1, vcc
	v_lshlrev_b32_e32 v1, 2, v1
	ds_bpermute_b32 v1, v1, v243
	v_readlane_b32 s65, v247, 54
	v_readlane_b32 s66, v247, 55
	v_readlane_b32 s67, v247, 56
	v_readlane_b32 s68, v247, 57
	s_waitcnt lgkmcnt(0)
	v_add_f32_e32 v1, v243, v1
	v_div_scale_f32 v2, s[0:1], v1, v1, 1.0
	v_rcp_f32_e32 v3, v2
	v_readlane_b32 s69, v247, 58
	v_readlane_b32 s70, v247, 59
	v_readlane_b32 s71, v247, 60
	v_fma_f32 v4, -v2, v3, 1.0
	v_fmac_f32_e32 v3, v4, v3
	v_div_scale_f32 v4, vcc, 1.0, v1, 1.0
	v_mul_f32_e32 v5, v4, v3
	v_fma_f32 v6, -v2, v5, v4
	v_fmac_f32_e32 v5, v6, v3
	v_fma_f32 v2, -v2, v5, v4
	v_div_fmas_f32 v2, v2, v3, v5
	v_lshlrev_b32_e32 v4, 1, v151
	v_mov_b32_e32 v5, v0
	v_lshl_add_u64 v[4:5], v[152:153], 0, v[4:5]
	global_load_dwordx2 v[6:7], v[4:5], off offset:1536
	global_load_dwordx2 v[154:155], v[4:5], off offset:1552
	global_load_dwordx2 v[156:157], v[4:5], off offset:1568
	global_load_dwordx2 v[158:159], v[4:5], off offset:1584
	global_load_dwordx2 v[160:161], v[4:5], off offset:1600
	global_load_dwordx2 v[162:163], v[4:5], off offset:1616
	global_load_dwordx2 v[164:165], v[4:5], off offset:1632
	global_load_dwordx2 v[166:167], v[4:5], off offset:1648
	v_div_fixup_f32 v2, v2, v1, 1.0
	v_pk_mul_f32 v[12:13], v[32:33], v[2:3] op_sel_hi:[1,0]
	v_readlane_b32 s74, v247, 63
	v_readlane_b32 s75, v246, 0
	v_readlane_b32 s76, v246, 1
	v_readlane_b32 s77, v246, 2
	v_readlane_b32 s78, v246, 3
	v_readlane_b32 s79, v246, 4
	v_readlane_b32 s72, v246, 60
	v_readlane_b32 s73, v247, 62
	s_waitcnt vmcnt(0)
	v_lshlrev_b32_e32 v8, 16, v6
	v_mul_f32_e32 v1, 0xbfb8aa3b, v8
	v_exp_f32_e32 v1, v1
	v_and_b32_e32 v9, 0xffff0000, v6
	v_add_f32_e32 v1, 1.0, v1
	v_rcp_f32_e32 v10, v1
	v_mul_f32_e32 v1, 0xbfb8aa3b, v9
	v_exp_f32_e32 v1, v1
	s_nop 0
	v_add_f32_e32 v1, 1.0, v1
	v_rcp_f32_e32 v11, v1
	s_nop 0
	v_pk_mul_f32 v[8:9], v[10:11], v[8:9]
	s_nop 0
	v_pk_mul_f32 v[8:9], v[12:13], v[8:9]
	v_pk_mul_f32 v[12:13], v[34:35], v[2:3] op_sel_hi:[1,0]
	v_cvt_pk_bf16_f32 v6, v8, v9
	v_lshlrev_b32_e32 v8, 16, v7
	v_mul_f32_e32 v1, 0xbfb8aa3b, v8
	v_exp_f32_e32 v1, v1
	v_and_b32_e32 v9, 0xffff0000, v7
	v_add_f32_e32 v1, 1.0, v1
	v_rcp_f32_e32 v10, v1
	v_mul_f32_e32 v1, 0xbfb8aa3b, v9
	v_exp_f32_e32 v1, v1
	s_nop 0
	v_add_f32_e32 v1, 1.0, v1
	v_rcp_f32_e32 v11, v1
	s_nop 0
	v_pk_mul_f32 v[8:9], v[10:11], v[8:9]
	s_nop 0
	v_pk_mul_f32 v[8:9], v[12:13], v[8:9]
	v_pk_mul_f32 v[12:13], v[36:37], v[2:3] op_sel_hi:[1,0]
	v_cvt_pk_bf16_f32 v7, v8, v9
	global_store_dwordx2 v[4:5], v[6:7], off
	v_mov_b32_e32 v6, v154
	v_mov_b32_e32 v7, v155
	v_lshlrev_b32_e32 v8, 16, v6
	v_mul_f32_e32 v1, 0xbfb8aa3b, v8
	v_exp_f32_e32 v1, v1
	v_and_b32_e32 v9, 0xffff0000, v6
	v_add_f32_e32 v1, 1.0, v1
	v_rcp_f32_e32 v10, v1
	v_mul_f32_e32 v1, 0xbfb8aa3b, v9
	v_exp_f32_e32 v1, v1
	s_nop 0
	v_add_f32_e32 v1, 1.0, v1
	v_rcp_f32_e32 v11, v1
	s_nop 0
	v_pk_mul_f32 v[8:9], v[10:11], v[8:9]
	s_nop 0
	v_pk_mul_f32 v[8:9], v[12:13], v[8:9]
	v_pk_mul_f32 v[12:13], v[38:39], v[2:3] op_sel_hi:[1,0]
	v_cvt_pk_bf16_f32 v6, v8, v9
	v_lshlrev_b32_e32 v8, 16, v7
	v_mul_f32_e32 v1, 0xbfb8aa3b, v8
	v_exp_f32_e32 v1, v1
	v_and_b32_e32 v9, 0xffff0000, v7
	v_add_f32_e32 v1, 1.0, v1
	v_rcp_f32_e32 v10, v1
	v_mul_f32_e32 v1, 0xbfb8aa3b, v9
	v_exp_f32_e32 v1, v1
	s_nop 0
	v_add_f32_e32 v1, 1.0, v1
	v_rcp_f32_e32 v11, v1
	s_nop 0
	v_pk_mul_f32 v[8:9], v[10:11], v[8:9]
	s_nop 0
	v_pk_mul_f32 v[8:9], v[12:13], v[8:9]
	v_pk_mul_f32 v[12:13], v[40:41], v[2:3] op_sel_hi:[1,0]
	v_cvt_pk_bf16_f32 v7, v8, v9
	global_store_dwordx2 v[4:5], v[6:7], off offset:16
	v_mov_b32_e32 v6, v156
	v_mov_b32_e32 v7, v157
	v_lshlrev_b32_e32 v8, 16, v6
	v_mul_f32_e32 v1, 0xbfb8aa3b, v8
	v_exp_f32_e32 v1, v1
	v_and_b32_e32 v9, 0xffff0000, v6
	v_add_f32_e32 v1, 1.0, v1
	v_rcp_f32_e32 v10, v1
	v_mul_f32_e32 v1, 0xbfb8aa3b, v9
	v_exp_f32_e32 v1, v1
	s_nop 0
	v_add_f32_e32 v1, 1.0, v1
	v_rcp_f32_e32 v11, v1
	s_nop 0
	v_pk_mul_f32 v[8:9], v[10:11], v[8:9]
	s_nop 0
	v_pk_mul_f32 v[8:9], v[12:13], v[8:9]
	v_pk_mul_f32 v[12:13], v[42:43], v[2:3] op_sel_hi:[1,0]
	v_cvt_pk_bf16_f32 v6, v8, v9
	v_lshlrev_b32_e32 v8, 16, v7
	v_mul_f32_e32 v1, 0xbfb8aa3b, v8
	v_exp_f32_e32 v1, v1
	v_and_b32_e32 v9, 0xffff0000, v7
	v_add_f32_e32 v1, 1.0, v1
	v_rcp_f32_e32 v10, v1
	v_mul_f32_e32 v1, 0xbfb8aa3b, v9
	v_exp_f32_e32 v1, v1
	s_nop 0
	v_add_f32_e32 v1, 1.0, v1
	v_rcp_f32_e32 v11, v1
	s_nop 0
	v_pk_mul_f32 v[8:9], v[10:11], v[8:9]
	s_nop 0
	v_pk_mul_f32 v[8:9], v[12:13], v[8:9]
	v_pk_mul_f32 v[12:13], v[44:45], v[2:3] op_sel_hi:[1,0]
	v_cvt_pk_bf16_f32 v7, v8, v9
	global_store_dwordx2 v[4:5], v[6:7], off offset:32
	v_mov_b32_e32 v6, v158
	v_mov_b32_e32 v7, v159
	v_lshlrev_b32_e32 v8, 16, v6
	v_mul_f32_e32 v1, 0xbfb8aa3b, v8
	v_exp_f32_e32 v1, v1
	v_and_b32_e32 v9, 0xffff0000, v6
	v_add_f32_e32 v1, 1.0, v1
	v_rcp_f32_e32 v10, v1
	v_mul_f32_e32 v1, 0xbfb8aa3b, v9
	v_exp_f32_e32 v1, v1
	s_nop 0
	v_add_f32_e32 v1, 1.0, v1
	v_rcp_f32_e32 v11, v1
	s_nop 0
	v_pk_mul_f32 v[8:9], v[10:11], v[8:9]
	s_nop 0
	v_pk_mul_f32 v[8:9], v[12:13], v[8:9]
	v_pk_mul_f32 v[12:13], v[46:47], v[2:3] op_sel_hi:[1,0]
	v_cvt_pk_bf16_f32 v6, v8, v9
	v_lshlrev_b32_e32 v8, 16, v7
	v_mul_f32_e32 v1, 0xbfb8aa3b, v8
	v_exp_f32_e32 v1, v1
	v_and_b32_e32 v9, 0xffff0000, v7
	v_add_f32_e32 v1, 1.0, v1
	v_rcp_f32_e32 v10, v1
	v_mul_f32_e32 v1, 0xbfb8aa3b, v9
	v_exp_f32_e32 v1, v1
	s_nop 0
	v_add_f32_e32 v1, 1.0, v1
	v_rcp_f32_e32 v11, v1
	s_nop 0
	v_pk_mul_f32 v[8:9], v[10:11], v[8:9]
	s_nop 0
	v_pk_mul_f32 v[8:9], v[12:13], v[8:9]
	v_pk_mul_f32 v[12:13], v[16:17], v[2:3] op_sel_hi:[1,0]
	v_cvt_pk_bf16_f32 v7, v8, v9
	global_store_dwordx2 v[4:5], v[6:7], off offset:48
	v_mov_b32_e32 v6, v160
	v_mov_b32_e32 v7, v161
	v_lshlrev_b32_e32 v8, 16, v6
	v_mul_f32_e32 v1, 0xbfb8aa3b, v8
	v_exp_f32_e32 v1, v1
	v_and_b32_e32 v9, 0xffff0000, v6
	v_add_f32_e32 v1, 1.0, v1
	v_rcp_f32_e32 v10, v1
	v_mul_f32_e32 v1, 0xbfb8aa3b, v9
	v_exp_f32_e32 v1, v1
	s_nop 0
	v_add_f32_e32 v1, 1.0, v1
	v_rcp_f32_e32 v11, v1
	s_nop 0
	v_pk_mul_f32 v[8:9], v[10:11], v[8:9]
	s_nop 0
	v_pk_mul_f32 v[8:9], v[12:13], v[8:9]
	v_pk_mul_f32 v[12:13], v[18:19], v[2:3] op_sel_hi:[1,0]
	v_cvt_pk_bf16_f32 v6, v8, v9
	v_lshlrev_b32_e32 v8, 16, v7
	v_mul_f32_e32 v1, 0xbfb8aa3b, v8
	v_exp_f32_e32 v1, v1
	v_and_b32_e32 v9, 0xffff0000, v7
	v_add_f32_e32 v1, 1.0, v1
	v_rcp_f32_e32 v10, v1
	v_mul_f32_e32 v1, 0xbfb8aa3b, v9
	v_exp_f32_e32 v1, v1
	s_nop 0
	v_add_f32_e32 v1, 1.0, v1
	v_rcp_f32_e32 v11, v1
	s_nop 0
	v_pk_mul_f32 v[8:9], v[10:11], v[8:9]
	s_nop 0
	v_pk_mul_f32 v[8:9], v[12:13], v[8:9]
	v_pk_mul_f32 v[12:13], v[20:21], v[2:3] op_sel_hi:[1,0]
	v_cvt_pk_bf16_f32 v7, v8, v9
	global_store_dwordx2 v[4:5], v[6:7], off offset:64
	v_mov_b32_e32 v6, v162
	v_mov_b32_e32 v7, v163
	v_lshlrev_b32_e32 v8, 16, v6
	v_mul_f32_e32 v1, 0xbfb8aa3b, v8
	v_exp_f32_e32 v1, v1
	v_and_b32_e32 v9, 0xffff0000, v6
	v_add_f32_e32 v1, 1.0, v1
	v_rcp_f32_e32 v10, v1
	v_mul_f32_e32 v1, 0xbfb8aa3b, v9
	v_exp_f32_e32 v1, v1
	s_nop 0
	v_add_f32_e32 v1, 1.0, v1
	v_rcp_f32_e32 v11, v1
	s_nop 0
	v_pk_mul_f32 v[8:9], v[10:11], v[8:9]
	s_nop 0
	v_pk_mul_f32 v[8:9], v[12:13], v[8:9]
	v_pk_mul_f32 v[12:13], v[22:23], v[2:3] op_sel_hi:[1,0]
	v_cvt_pk_bf16_f32 v6, v8, v9
	v_lshlrev_b32_e32 v8, 16, v7
	v_mul_f32_e32 v1, 0xbfb8aa3b, v8
	v_exp_f32_e32 v1, v1
	v_and_b32_e32 v9, 0xffff0000, v7
	v_add_f32_e32 v1, 1.0, v1
	v_rcp_f32_e32 v10, v1
	v_mul_f32_e32 v1, 0xbfb8aa3b, v9
	v_exp_f32_e32 v1, v1
	s_nop 0
	v_add_f32_e32 v1, 1.0, v1
	v_rcp_f32_e32 v11, v1
	s_nop 0
	v_pk_mul_f32 v[8:9], v[10:11], v[8:9]
	s_nop 0
	v_pk_mul_f32 v[8:9], v[12:13], v[8:9]
	v_pk_mul_f32 v[12:13], v[24:25], v[2:3] op_sel_hi:[1,0]
	v_cvt_pk_bf16_f32 v7, v8, v9
	global_store_dwordx2 v[4:5], v[6:7], off offset:80
	v_mov_b32_e32 v6, v164
	v_mov_b32_e32 v7, v165
	v_lshlrev_b32_e32 v8, 16, v6
	v_mul_f32_e32 v1, 0xbfb8aa3b, v8
	v_exp_f32_e32 v1, v1
	v_and_b32_e32 v9, 0xffff0000, v6
	v_add_f32_e32 v1, 1.0, v1
	v_rcp_f32_e32 v10, v1
	v_mul_f32_e32 v1, 0xbfb8aa3b, v9
	v_exp_f32_e32 v1, v1
	s_nop 0
	v_add_f32_e32 v1, 1.0, v1
	v_rcp_f32_e32 v11, v1
	s_nop 0
	v_pk_mul_f32 v[8:9], v[10:11], v[8:9]
	s_nop 0
	v_pk_mul_f32 v[8:9], v[12:13], v[8:9]
	v_pk_mul_f32 v[12:13], v[26:27], v[2:3] op_sel_hi:[1,0]
	v_cvt_pk_bf16_f32 v6, v8, v9
	v_lshlrev_b32_e32 v8, 16, v7
	v_mul_f32_e32 v1, 0xbfb8aa3b, v8
	v_exp_f32_e32 v1, v1
	v_and_b32_e32 v9, 0xffff0000, v7
	v_add_f32_e32 v1, 1.0, v1
	v_rcp_f32_e32 v10, v1
	v_mul_f32_e32 v1, 0xbfb8aa3b, v9
	v_exp_f32_e32 v1, v1
	s_nop 0
	v_add_f32_e32 v1, 1.0, v1
	v_rcp_f32_e32 v11, v1
	s_nop 0
	v_pk_mul_f32 v[8:9], v[10:11], v[8:9]
	s_nop 0
	v_pk_mul_f32 v[8:9], v[12:13], v[8:9]
	v_pk_mul_f32 v[12:13], v[28:29], v[2:3] op_sel_hi:[1,0]
	v_cvt_pk_bf16_f32 v7, v8, v9
	global_store_dwordx2 v[4:5], v[6:7], off offset:96
	v_mov_b32_e32 v6, v166
	v_mov_b32_e32 v7, v167
	v_pk_mul_f32 v[2:3], v[30:31], v[2:3] op_sel_hi:[1,0]
	v_lshlrev_b32_e32 v8, 16, v6
	v_mul_f32_e32 v1, 0xbfb8aa3b, v8
	v_exp_f32_e32 v1, v1
	v_and_b32_e32 v9, 0xffff0000, v6
	v_add_f32_e32 v1, 1.0, v1
	v_rcp_f32_e32 v10, v1
	v_mul_f32_e32 v1, 0xbfb8aa3b, v9
	v_exp_f32_e32 v1, v1
	s_nop 0
	v_add_f32_e32 v1, 1.0, v1
	v_rcp_f32_e32 v11, v1
	s_nop 0
	v_pk_mul_f32 v[8:9], v[10:11], v[8:9]
	s_nop 0
	v_pk_mul_f32 v[8:9], v[12:13], v[8:9]
	s_nop 0
	v_cvt_pk_bf16_f32 v6, v8, v9
	v_lshlrev_b32_e32 v8, 16, v7
	v_mul_f32_e32 v1, 0xbfb8aa3b, v8
	v_exp_f32_e32 v1, v1
	v_and_b32_e32 v9, 0xffff0000, v7
	v_add_f32_e32 v1, 1.0, v1
	v_rcp_f32_e32 v10, v1
	v_mul_f32_e32 v1, 0xbfb8aa3b, v9
	v_exp_f32_e32 v1, v1
	s_nop 0
	v_add_f32_e32 v1, 1.0, v1
	v_rcp_f32_e32 v11, v1
	s_nop 0
	v_pk_mul_f32 v[8:9], v[10:11], v[8:9]
	s_nop 0
	v_pk_mul_f32 v[2:3], v[2:3], v[8:9]
	s_nop 0
	v_cvt_pk_bf16_f32 v7, v2, v3
	global_store_dwordx2 v[4:5], v[6:7], off offset:112
